# merge: 8 gate loads of the gating epilogue hoisted two K-steps ahead, last K-step unrolled, gating interleaved with last 16 MFMAs
# speedup vs baseline: 1.0186x; 1.0057x over previous
.LBB0_1010:
	s_add_u32 s80, s18, 0x9504000
	s_addc_u32 s81, s19, 0
	s_add_u32 s86, s80, 0x1f0000
	s_addc_u32 s87, s81, 0
	s_add_u32 s96, s6, 0x1404000
	s_addc_u32 s97, s7, 0
	s_add_u32 s98, s96, 0x10000
	s_addc_u32 s99, s97, 0
	v_subrev_u32_e32 v190, s18, v190
	v_add_u32_e32 v191, 0xf8000, v190
	v_subrev_u32_e32 v188, s6, v188
	v_add_u32_e32 v207, 0xa000, v206
	global_load_dwordx4 v[228:231], v190, s[80:81] offset:128
	global_load_dwordx4 v[232:235], v191, s[80:81] offset:128
	global_load_dwordx4 v[236:239], v190, s[86:87] offset:128
	global_load_dwordx4 v[240:243], v191, s[86:87] offset:128
	global_load_dwordx4 v[244:247], v188, s[96:97] offset:128
	global_load_dwordx4 v[248:251], v188, s[98:99] offset:128
	global_load_dwordx4 v[66:69], v190, s[80:81] offset:256
	global_load_dwordx4 v[70:73], v191, s[80:81] offset:256
	global_load_dwordx4 v[74:77], v190, s[86:87] offset:256
	global_load_dwordx4 v[78:81], v191, s[86:87] offset:256
	global_load_dwordx4 v[82:85], v188, s[96:97] offset:256
	global_load_dwordx4 v[86:89], v188, s[98:99] offset:256
	ds_read_b128 v[90:93], v119 offset:0
	ds_read_b128 v[208:211], v205 offset:0
	ds_read_b128 v[212:215], v119 offset:2560
	ds_read_b128 v[216:219], v119 offset:5120
	ds_read_b128 v[220:223], v119 offset:7680
	s_waitcnt lgkmcnt(3)
	v_mfma_f32_16x16x32_bf16 v[6:9], v[90:93], v[208:211], v[6:9]
	s_waitcnt lgkmcnt(2)
	v_mfma_f32_16x16x32_bf16 v[30:33], v[212:215], v[208:211], v[30:33]
	s_waitcnt vmcnt(11)
	ds_write_b128 v207, v[228:231] offset:0
	s_waitcnt lgkmcnt(2)
	v_mfma_f32_16x16x32_bf16 v[38:41], v[216:219], v[208:211], v[38:41]
	s_waitcnt lgkmcnt(1)
	v_mfma_f32_16x16x32_bf16 v[42:45], v[220:223], v[208:211], v[42:45]
	ds_read_b128 v[208:211], v205 offset:2560
	s_waitcnt lgkmcnt(0)
	v_mfma_f32_16x16x32_bf16 v[46:49], v[90:93], v[208:211], v[46:49]
	v_mfma_f32_16x16x32_bf16 v[26:29], v[212:215], v[208:211], v[26:29]
	s_waitcnt vmcnt(10)
	ds_write_b128 v207, v[232:235] offset:10240
	v_mfma_f32_16x16x32_bf16 v[14:17], v[216:219], v[208:211], v[14:17]
	v_mfma_f32_16x16x32_bf16 v[10:13], v[220:223], v[208:211], v[10:13]
	ds_read_b128 v[208:211], v205 offset:5120
	s_waitcnt lgkmcnt(0)
	v_mfma_f32_16x16x32_bf16 v[34:37], v[90:93], v[208:211], v[34:37]
	v_mfma_f32_16x16x32_bf16 v[22:25], v[212:215], v[208:211], v[22:25]
	s_waitcnt vmcnt(9)
	ds_write_b128 v207, v[236:239] offset:20480
	v_mfma_f32_16x16x32_bf16 v[18:21], v[216:219], v[208:211], v[18:21]
	v_mfma_f32_16x16x32_bf16 v[62:65], v[220:223], v[208:211], v[62:65]
	ds_read_b128 v[208:211], v205 offset:7680
	s_waitcnt lgkmcnt(0)
	v_mfma_f32_16x16x32_bf16 v[58:61], v[90:93], v[208:211], v[58:61]
	ds_read_b128 v[90:93], v119 offset:64
	v_mfma_f32_16x16x32_bf16 v[54:57], v[212:215], v[208:211], v[54:57]
	s_waitcnt vmcnt(8)
	ds_write_b128 v207, v[240:243] offset:30720
	ds_read_b128 v[212:215], v119 offset:2624
	v_mfma_f32_16x16x32_bf16 v[50:53], v[216:219], v[208:211], v[50:53]
	ds_read_b128 v[216:219], v119 offset:5184
	v_mfma_f32_16x16x32_bf16 v[2:5], v[220:223], v[208:211], v[2:5]
	ds_read_b128 v[220:223], v119 offset:7744
	ds_read_b128 v[208:211], v205 offset:64
	ds_read_b128 v[224:227], v205 offset:7744
	s_waitcnt lgkmcnt(1)
	v_mfma_f32_16x16x32_bf16 v[6:9], v[90:93], v[208:211], v[6:9]
	v_mfma_f32_16x16x32_bf16 v[30:33], v[212:215], v[208:211], v[30:33]
	s_waitcnt vmcnt(7)
	ds_write_b128 v0, v[244:247] offset:20480
	v_mfma_f32_16x16x32_bf16 v[38:41], v[216:219], v[208:211], v[38:41]
	v_mfma_f32_16x16x32_bf16 v[42:45], v[220:223], v[208:211], v[42:45]
	ds_read_b128 v[208:211], v205 offset:2624
	s_waitcnt lgkmcnt(0)
	v_mfma_f32_16x16x32_bf16 v[46:49], v[90:93], v[208:211], v[46:49]
	v_mfma_f32_16x16x32_bf16 v[26:29], v[212:215], v[208:211], v[26:29]
	s_waitcnt vmcnt(6)
	ds_write_b128 v0, v[248:251] offset:30720
	v_mfma_f32_16x16x32_bf16 v[14:17], v[216:219], v[208:211], v[14:17]
	v_mfma_f32_16x16x32_bf16 v[10:13], v[220:223], v[208:211], v[10:13]
	ds_read_b128 v[208:211], v205 offset:5184
	s_waitcnt lgkmcnt(0)
	v_mfma_f32_16x16x32_bf16 v[34:37], v[90:93], v[208:211], v[34:37]
	v_mfma_f32_16x16x32_bf16 v[22:25], v[212:215], v[208:211], v[22:25]
	v_mfma_f32_16x16x32_bf16 v[18:21], v[216:219], v[208:211], v[18:21]
	v_mfma_f32_16x16x32_bf16 v[62:65], v[220:223], v[208:211], v[62:65]
	v_mfma_f32_16x16x32_bf16 v[58:61], v[90:93], v[224:227], v[58:61]
	s_waitcnt lgkmcnt(0)
	v_mfma_f32_16x16x32_bf16 v[54:57], v[212:215], v[224:227], v[54:57]
	s_barrier
	v_mfma_f32_16x16x32_bf16 v[50:53], v[216:219], v[224:227], v[50:53]
	v_mfma_f32_16x16x32_bf16 v[2:5], v[220:223], v[224:227], v[2:5]
	global_load_dwordx4 v[228:231], v190, s[80:81] offset:384
	global_load_dwordx4 v[232:235], v191, s[80:81] offset:384
	global_load_dwordx4 v[236:239], v190, s[86:87] offset:384
	global_load_dwordx4 v[240:243], v191, s[86:87] offset:384
	global_load_dwordx4 v[244:247], v188, s[96:97] offset:384
	global_load_dwordx4 v[248:251], v188, s[98:99] offset:384
	ds_read_b128 v[90:93], v119 offset:20480
	ds_read_b128 v[208:211], v205 offset:40960
	ds_read_b128 v[212:215], v119 offset:23040
	ds_read_b128 v[216:219], v119 offset:25600
	ds_read_b128 v[220:223], v119 offset:28160
	s_waitcnt lgkmcnt(3)
	v_mfma_f32_16x16x32_bf16 v[6:9], v[90:93], v[208:211], v[6:9]
	s_waitcnt lgkmcnt(2)
	v_mfma_f32_16x16x32_bf16 v[30:33], v[212:215], v[208:211], v[30:33]
	s_waitcnt vmcnt(11)
	ds_write_b128 v206, v[66:69] offset:0
	s_waitcnt lgkmcnt(2)
	v_mfma_f32_16x16x32_bf16 v[38:41], v[216:219], v[208:211], v[38:41]
	s_waitcnt lgkmcnt(1)
	v_mfma_f32_16x16x32_bf16 v[42:45], v[220:223], v[208:211], v[42:45]
	ds_read_b128 v[208:211], v205 offset:43520
	s_waitcnt lgkmcnt(0)
	v_mfma_f32_16x16x32_bf16 v[46:49], v[90:93], v[208:211], v[46:49]
	v_mfma_f32_16x16x32_bf16 v[26:29], v[212:215], v[208:211], v[26:29]
	s_waitcnt vmcnt(10)
	ds_write_b128 v206, v[70:73] offset:10240
	v_mfma_f32_16x16x32_bf16 v[14:17], v[216:219], v[208:211], v[14:17]
	v_mfma_f32_16x16x32_bf16 v[10:13], v[220:223], v[208:211], v[10:13]
	ds_read_b128 v[208:211], v205 offset:46080
	s_waitcnt lgkmcnt(0)
	v_mfma_f32_16x16x32_bf16 v[34:37], v[90:93], v[208:211], v[34:37]
	v_mfma_f32_16x16x32_bf16 v[22:25], v[212:215], v[208:211], v[22:25]
	s_waitcnt vmcnt(9)
	ds_write_b128 v206, v[74:77] offset:20480
	v_mfma_f32_16x16x32_bf16 v[18:21], v[216:219], v[208:211], v[18:21]
	v_mfma_f32_16x16x32_bf16 v[62:65], v[220:223], v[208:211], v[62:65]
	ds_read_b128 v[208:211], v205 offset:48640
	s_waitcnt lgkmcnt(0)
	v_mfma_f32_16x16x32_bf16 v[58:61], v[90:93], v[208:211], v[58:61]
	ds_read_b128 v[90:93], v119 offset:20544
	v_mfma_f32_16x16x32_bf16 v[54:57], v[212:215], v[208:211], v[54:57]
	s_waitcnt vmcnt(8)
	ds_write_b128 v206, v[78:81] offset:30720
	ds_read_b128 v[212:215], v119 offset:23104
	v_mfma_f32_16x16x32_bf16 v[50:53], v[216:219], v[208:211], v[50:53]
	ds_read_b128 v[216:219], v119 offset:25664
	v_mfma_f32_16x16x32_bf16 v[2:5], v[220:223], v[208:211], v[2:5]
	ds_read_b128 v[220:223], v119 offset:28224
	ds_read_b128 v[208:211], v205 offset:41024
	ds_read_b128 v[224:227], v205 offset:48704
	s_waitcnt lgkmcnt(1)
	v_mfma_f32_16x16x32_bf16 v[6:9], v[90:93], v[208:211], v[6:9]
	v_mfma_f32_16x16x32_bf16 v[30:33], v[212:215], v[208:211], v[30:33]
	s_waitcnt vmcnt(7)
	ds_write_b128 v0, v[82:85] offset:0
	v_mfma_f32_16x16x32_bf16 v[38:41], v[216:219], v[208:211], v[38:41]
	v_mfma_f32_16x16x32_bf16 v[42:45], v[220:223], v[208:211], v[42:45]
	ds_read_b128 v[208:211], v205 offset:43584
	s_waitcnt lgkmcnt(0)
	v_mfma_f32_16x16x32_bf16 v[46:49], v[90:93], v[208:211], v[46:49]
	v_mfma_f32_16x16x32_bf16 v[26:29], v[212:215], v[208:211], v[26:29]
	s_waitcnt vmcnt(6)
	ds_write_b128 v0, v[86:89] offset:10240
	v_mfma_f32_16x16x32_bf16 v[14:17], v[216:219], v[208:211], v[14:17]
	v_mfma_f32_16x16x32_bf16 v[10:13], v[220:223], v[208:211], v[10:13]
	ds_read_b128 v[208:211], v205 offset:46144
	s_waitcnt lgkmcnt(0)
	v_mfma_f32_16x16x32_bf16 v[34:37], v[90:93], v[208:211], v[34:37]
	v_mfma_f32_16x16x32_bf16 v[22:25], v[212:215], v[208:211], v[22:25]
	v_mfma_f32_16x16x32_bf16 v[18:21], v[216:219], v[208:211], v[18:21]
	v_mfma_f32_16x16x32_bf16 v[62:65], v[220:223], v[208:211], v[62:65]
	v_mfma_f32_16x16x32_bf16 v[58:61], v[90:93], v[224:227], v[58:61]
	s_waitcnt lgkmcnt(0)
	v_mfma_f32_16x16x32_bf16 v[54:57], v[212:215], v[224:227], v[54:57]
	s_barrier
	v_mfma_f32_16x16x32_bf16 v[50:53], v[216:219], v[224:227], v[50:53]
	v_mfma_f32_16x16x32_bf16 v[2:5], v[220:223], v[224:227], v[2:5]
	global_load_dwordx4 v[66:69], v190, s[80:81] offset:512
	global_load_dwordx4 v[70:73], v191, s[80:81] offset:512
	global_load_dwordx4 v[74:77], v190, s[86:87] offset:512
	global_load_dwordx4 v[78:81], v191, s[86:87] offset:512
	global_load_dwordx4 v[82:85], v188, s[96:97] offset:512
	global_load_dwordx4 v[86:89], v188, s[98:99] offset:512
	ds_read_b128 v[90:93], v119 offset:0
	ds_read_b128 v[208:211], v205 offset:0
	ds_read_b128 v[212:215], v119 offset:2560
	ds_read_b128 v[216:219], v119 offset:5120
	ds_read_b128 v[220:223], v119 offset:7680
	s_waitcnt lgkmcnt(3)
	v_mfma_f32_16x16x32_bf16 v[6:9], v[90:93], v[208:211], v[6:9]
	s_waitcnt lgkmcnt(2)
	v_mfma_f32_16x16x32_bf16 v[30:33], v[212:215], v[208:211], v[30:33]
	s_waitcnt vmcnt(11)
	ds_write_b128 v207, v[228:231] offset:0
	s_waitcnt lgkmcnt(2)
	v_mfma_f32_16x16x32_bf16 v[38:41], v[216:219], v[208:211], v[38:41]
	s_waitcnt lgkmcnt(1)
	v_mfma_f32_16x16x32_bf16 v[42:45], v[220:223], v[208:211], v[42:45]
	ds_read_b128 v[208:211], v205 offset:2560
	s_waitcnt lgkmcnt(0)
	v_mfma_f32_16x16x32_bf16 v[46:49], v[90:93], v[208:211], v[46:49]
	v_mfma_f32_16x16x32_bf16 v[26:29], v[212:215], v[208:211], v[26:29]
	s_waitcnt vmcnt(10)
	ds_write_b128 v207, v[232:235] offset:10240
	v_mfma_f32_16x16x32_bf16 v[14:17], v[216:219], v[208:211], v[14:17]
	v_mfma_f32_16x16x32_bf16 v[10:13], v[220:223], v[208:211], v[10:13]
	ds_read_b128 v[208:211], v205 offset:5120
	s_waitcnt lgkmcnt(0)
	v_mfma_f32_16x16x32_bf16 v[34:37], v[90:93], v[208:211], v[34:37]
	v_mfma_f32_16x16x32_bf16 v[22:25], v[212:215], v[208:211], v[22:25]
	s_waitcnt vmcnt(9)
	ds_write_b128 v207, v[236:239] offset:20480
	v_mfma_f32_16x16x32_bf16 v[18:21], v[216:219], v[208:211], v[18:21]
	v_mfma_f32_16x16x32_bf16 v[62:65], v[220:223], v[208:211], v[62:65]
	ds_read_b128 v[208:211], v205 offset:7680
	s_waitcnt lgkmcnt(0)
	v_mfma_f32_16x16x32_bf16 v[58:61], v[90:93], v[208:211], v[58:61]
	ds_read_b128 v[90:93], v119 offset:64
	v_mfma_f32_16x16x32_bf16 v[54:57], v[212:215], v[208:211], v[54:57]
	s_waitcnt vmcnt(8)
	ds_write_b128 v207, v[240:243] offset:30720
	ds_read_b128 v[212:215], v119 offset:2624
	v_mfma_f32_16x16x32_bf16 v[50:53], v[216:219], v[208:211], v[50:53]
	ds_read_b128 v[216:219], v119 offset:5184
	v_mfma_f32_16x16x32_bf16 v[2:5], v[220:223], v[208:211], v[2:5]
	ds_read_b128 v[220:223], v119 offset:7744
	ds_read_b128 v[208:211], v205 offset:64
	ds_read_b128 v[224:227], v205 offset:7744
	s_waitcnt lgkmcnt(1)
	v_mfma_f32_16x16x32_bf16 v[6:9], v[90:93], v[208:211], v[6:9]
	v_mfma_f32_16x16x32_bf16 v[30:33], v[212:215], v[208:211], v[30:33]
	s_waitcnt vmcnt(7)
	ds_write_b128 v0, v[244:247] offset:20480
	v_mfma_f32_16x16x32_bf16 v[38:41], v[216:219], v[208:211], v[38:41]
	v_mfma_f32_16x16x32_bf16 v[42:45], v[220:223], v[208:211], v[42:45]
	ds_read_b128 v[208:211], v205 offset:2624
	s_waitcnt lgkmcnt(0)
	v_mfma_f32_16x16x32_bf16 v[46:49], v[90:93], v[208:211], v[46:49]
	v_mfma_f32_16x16x32_bf16 v[26:29], v[212:215], v[208:211], v[26:29]
	s_waitcnt vmcnt(6)
	ds_write_b128 v0, v[248:251] offset:30720
	v_mfma_f32_16x16x32_bf16 v[14:17], v[216:219], v[208:211], v[14:17]
	v_mfma_f32_16x16x32_bf16 v[10:13], v[220:223], v[208:211], v[10:13]
	ds_read_b128 v[208:211], v205 offset:5184
	s_waitcnt lgkmcnt(0)
	v_mfma_f32_16x16x32_bf16 v[34:37], v[90:93], v[208:211], v[34:37]
	v_mfma_f32_16x16x32_bf16 v[22:25], v[212:215], v[208:211], v[22:25]
	v_mfma_f32_16x16x32_bf16 v[18:21], v[216:219], v[208:211], v[18:21]
	v_mfma_f32_16x16x32_bf16 v[62:65], v[220:223], v[208:211], v[62:65]
	v_mfma_f32_16x16x32_bf16 v[58:61], v[90:93], v[224:227], v[58:61]
	s_waitcnt lgkmcnt(0)
	v_mfma_f32_16x16x32_bf16 v[54:57], v[212:215], v[224:227], v[54:57]
	s_barrier
	v_mfma_f32_16x16x32_bf16 v[50:53], v[216:219], v[224:227], v[50:53]
	v_mfma_f32_16x16x32_bf16 v[2:5], v[220:223], v[224:227], v[2:5]
	global_load_dwordx4 v[228:231], v190, s[80:81] offset:640
	global_load_dwordx4 v[232:235], v191, s[80:81] offset:640
	global_load_dwordx4 v[236:239], v190, s[86:87] offset:640
	global_load_dwordx4 v[240:243], v191, s[86:87] offset:640
	global_load_dwordx4 v[244:247], v188, s[96:97] offset:640
	global_load_dwordx4 v[248:251], v188, s[98:99] offset:640
	ds_read_b128 v[90:93], v119 offset:20480
	ds_read_b128 v[208:211], v205 offset:40960
	ds_read_b128 v[212:215], v119 offset:23040
	ds_read_b128 v[216:219], v119 offset:25600
	ds_read_b128 v[220:223], v119 offset:28160
	s_waitcnt lgkmcnt(3)
	v_mfma_f32_16x16x32_bf16 v[6:9], v[90:93], v[208:211], v[6:9]
	s_waitcnt lgkmcnt(2)
	v_mfma_f32_16x16x32_bf16 v[30:33], v[212:215], v[208:211], v[30:33]
	s_waitcnt vmcnt(11)
	ds_write_b128 v206, v[66:69] offset:0
	s_waitcnt lgkmcnt(2)
	v_mfma_f32_16x16x32_bf16 v[38:41], v[216:219], v[208:211], v[38:41]
	s_waitcnt lgkmcnt(1)
	v_mfma_f32_16x16x32_bf16 v[42:45], v[220:223], v[208:211], v[42:45]
	ds_read_b128 v[208:211], v205 offset:43520
	s_waitcnt lgkmcnt(0)
	v_mfma_f32_16x16x32_bf16 v[46:49], v[90:93], v[208:211], v[46:49]
	v_mfma_f32_16x16x32_bf16 v[26:29], v[212:215], v[208:211], v[26:29]
	s_waitcnt vmcnt(10)
	ds_write_b128 v206, v[70:73] offset:10240
	v_mfma_f32_16x16x32_bf16 v[14:17], v[216:219], v[208:211], v[14:17]
	v_mfma_f32_16x16x32_bf16 v[10:13], v[220:223], v[208:211], v[10:13]
	ds_read_b128 v[208:211], v205 offset:46080
	s_waitcnt lgkmcnt(0)
	v_mfma_f32_16x16x32_bf16 v[34:37], v[90:93], v[208:211], v[34:37]
	v_mfma_f32_16x16x32_bf16 v[22:25], v[212:215], v[208:211], v[22:25]
	s_waitcnt vmcnt(9)
	ds_write_b128 v206, v[74:77] offset:20480
	v_mfma_f32_16x16x32_bf16 v[18:21], v[216:219], v[208:211], v[18:21]
	v_mfma_f32_16x16x32_bf16 v[62:65], v[220:223], v[208:211], v[62:65]
	ds_read_b128 v[208:211], v205 offset:48640
	s_waitcnt lgkmcnt(0)
	v_mfma_f32_16x16x32_bf16 v[58:61], v[90:93], v[208:211], v[58:61]
	ds_read_b128 v[90:93], v119 offset:20544
	v_mfma_f32_16x16x32_bf16 v[54:57], v[212:215], v[208:211], v[54:57]
	s_waitcnt vmcnt(8)
	ds_write_b128 v206, v[78:81] offset:30720
	ds_read_b128 v[212:215], v119 offset:23104
	v_mfma_f32_16x16x32_bf16 v[50:53], v[216:219], v[208:211], v[50:53]
	ds_read_b128 v[216:219], v119 offset:25664
	v_mfma_f32_16x16x32_bf16 v[2:5], v[220:223], v[208:211], v[2:5]
	ds_read_b128 v[220:223], v119 offset:28224
	ds_read_b128 v[208:211], v205 offset:41024
	ds_read_b128 v[224:227], v205 offset:48704
	s_waitcnt lgkmcnt(1)
	v_mfma_f32_16x16x32_bf16 v[6:9], v[90:93], v[208:211], v[6:9]
	v_mfma_f32_16x16x32_bf16 v[30:33], v[212:215], v[208:211], v[30:33]
	s_waitcnt vmcnt(7)
	ds_write_b128 v0, v[82:85] offset:0
	v_mfma_f32_16x16x32_bf16 v[38:41], v[216:219], v[208:211], v[38:41]
	v_mfma_f32_16x16x32_bf16 v[42:45], v[220:223], v[208:211], v[42:45]
	ds_read_b128 v[208:211], v205 offset:43584
	s_waitcnt lgkmcnt(0)
	v_mfma_f32_16x16x32_bf16 v[46:49], v[90:93], v[208:211], v[46:49]
	v_mfma_f32_16x16x32_bf16 v[26:29], v[212:215], v[208:211], v[26:29]
	s_waitcnt vmcnt(6)
	ds_write_b128 v0, v[86:89] offset:10240
	v_mfma_f32_16x16x32_bf16 v[14:17], v[216:219], v[208:211], v[14:17]
	v_mfma_f32_16x16x32_bf16 v[10:13], v[220:223], v[208:211], v[10:13]
	ds_read_b128 v[208:211], v205 offset:46144
	s_waitcnt lgkmcnt(0)
	v_mfma_f32_16x16x32_bf16 v[34:37], v[90:93], v[208:211], v[34:37]
	v_mfma_f32_16x16x32_bf16 v[22:25], v[212:215], v[208:211], v[22:25]
	v_mfma_f32_16x16x32_bf16 v[18:21], v[216:219], v[208:211], v[18:21]
	v_mfma_f32_16x16x32_bf16 v[62:65], v[220:223], v[208:211], v[62:65]
	v_mfma_f32_16x16x32_bf16 v[58:61], v[90:93], v[224:227], v[58:61]
	s_waitcnt lgkmcnt(0)
	v_mfma_f32_16x16x32_bf16 v[54:57], v[212:215], v[224:227], v[54:57]
	s_barrier
	v_mfma_f32_16x16x32_bf16 v[50:53], v[216:219], v[224:227], v[50:53]
	v_mfma_f32_16x16x32_bf16 v[2:5], v[220:223], v[224:227], v[2:5]
	global_load_dwordx4 v[66:69], v190, s[80:81] offset:768
	global_load_dwordx4 v[70:73], v191, s[80:81] offset:768
	global_load_dwordx4 v[74:77], v190, s[86:87] offset:768
	global_load_dwordx4 v[78:81], v191, s[86:87] offset:768
	global_load_dwordx4 v[82:85], v188, s[96:97] offset:768
	global_load_dwordx4 v[86:89], v188, s[98:99] offset:768
	ds_read_b128 v[90:93], v119 offset:0
	ds_read_b128 v[208:211], v205 offset:0
	ds_read_b128 v[212:215], v119 offset:2560
	ds_read_b128 v[216:219], v119 offset:5120
	ds_read_b128 v[220:223], v119 offset:7680
	s_waitcnt lgkmcnt(3)
	v_mfma_f32_16x16x32_bf16 v[6:9], v[90:93], v[208:211], v[6:9]
	s_waitcnt lgkmcnt(2)
	v_mfma_f32_16x16x32_bf16 v[30:33], v[212:215], v[208:211], v[30:33]
	s_waitcnt vmcnt(11)
	ds_write_b128 v207, v[228:231] offset:0
	s_waitcnt lgkmcnt(2)
	v_mfma_f32_16x16x32_bf16 v[38:41], v[216:219], v[208:211], v[38:41]
	s_waitcnt lgkmcnt(1)
	v_mfma_f32_16x16x32_bf16 v[42:45], v[220:223], v[208:211], v[42:45]
	ds_read_b128 v[208:211], v205 offset:2560
	s_waitcnt lgkmcnt(0)
	v_mfma_f32_16x16x32_bf16 v[46:49], v[90:93], v[208:211], v[46:49]
	v_mfma_f32_16x16x32_bf16 v[26:29], v[212:215], v[208:211], v[26:29]
	s_waitcnt vmcnt(10)
	ds_write_b128 v207, v[232:235] offset:10240
	v_mfma_f32_16x16x32_bf16 v[14:17], v[216:219], v[208:211], v[14:17]
	v_mfma_f32_16x16x32_bf16 v[10:13], v[220:223], v[208:211], v[10:13]
	ds_read_b128 v[208:211], v205 offset:5120
	s_waitcnt lgkmcnt(0)
	v_mfma_f32_16x16x32_bf16 v[34:37], v[90:93], v[208:211], v[34:37]
	v_mfma_f32_16x16x32_bf16 v[22:25], v[212:215], v[208:211], v[22:25]
	s_waitcnt vmcnt(9)
	ds_write_b128 v207, v[236:239] offset:20480
	v_mfma_f32_16x16x32_bf16 v[18:21], v[216:219], v[208:211], v[18:21]
	v_mfma_f32_16x16x32_bf16 v[62:65], v[220:223], v[208:211], v[62:65]
	ds_read_b128 v[208:211], v205 offset:7680
	s_waitcnt lgkmcnt(0)
	v_mfma_f32_16x16x32_bf16 v[58:61], v[90:93], v[208:211], v[58:61]
	ds_read_b128 v[90:93], v119 offset:64
	v_mfma_f32_16x16x32_bf16 v[54:57], v[212:215], v[208:211], v[54:57]
	s_waitcnt vmcnt(8)
	ds_write_b128 v207, v[240:243] offset:30720
	ds_read_b128 v[212:215], v119 offset:2624
	v_mfma_f32_16x16x32_bf16 v[50:53], v[216:219], v[208:211], v[50:53]
	ds_read_b128 v[216:219], v119 offset:5184
	v_mfma_f32_16x16x32_bf16 v[2:5], v[220:223], v[208:211], v[2:5]
	ds_read_b128 v[220:223], v119 offset:7744
	ds_read_b128 v[208:211], v205 offset:64
	ds_read_b128 v[224:227], v205 offset:7744
	s_waitcnt lgkmcnt(1)
	v_mfma_f32_16x16x32_bf16 v[6:9], v[90:93], v[208:211], v[6:9]
	v_mfma_f32_16x16x32_bf16 v[30:33], v[212:215], v[208:211], v[30:33]
	s_waitcnt vmcnt(7)
	ds_write_b128 v0, v[244:247] offset:20480
	v_mfma_f32_16x16x32_bf16 v[38:41], v[216:219], v[208:211], v[38:41]
	v_mfma_f32_16x16x32_bf16 v[42:45], v[220:223], v[208:211], v[42:45]
	ds_read_b128 v[208:211], v205 offset:2624
	s_waitcnt lgkmcnt(0)
	v_mfma_f32_16x16x32_bf16 v[46:49], v[90:93], v[208:211], v[46:49]
	v_mfma_f32_16x16x32_bf16 v[26:29], v[212:215], v[208:211], v[26:29]
	s_waitcnt vmcnt(6)
	ds_write_b128 v0, v[248:251] offset:30720
	v_mfma_f32_16x16x32_bf16 v[14:17], v[216:219], v[208:211], v[14:17]
	v_mfma_f32_16x16x32_bf16 v[10:13], v[220:223], v[208:211], v[10:13]
	ds_read_b128 v[208:211], v205 offset:5184
	s_waitcnt lgkmcnt(0)
	v_mfma_f32_16x16x32_bf16 v[34:37], v[90:93], v[208:211], v[34:37]
	v_mfma_f32_16x16x32_bf16 v[22:25], v[212:215], v[208:211], v[22:25]
	v_mfma_f32_16x16x32_bf16 v[18:21], v[216:219], v[208:211], v[18:21]
	v_mfma_f32_16x16x32_bf16 v[62:65], v[220:223], v[208:211], v[62:65]
	v_mfma_f32_16x16x32_bf16 v[58:61], v[90:93], v[224:227], v[58:61]
	s_waitcnt lgkmcnt(0)
	v_mfma_f32_16x16x32_bf16 v[54:57], v[212:215], v[224:227], v[54:57]
	s_barrier
	v_mfma_f32_16x16x32_bf16 v[50:53], v[216:219], v[224:227], v[50:53]
	v_mfma_f32_16x16x32_bf16 v[2:5], v[220:223], v[224:227], v[2:5]
	global_load_dwordx4 v[228:231], v190, s[80:81] offset:896
	global_load_dwordx4 v[232:235], v191, s[80:81] offset:896
	global_load_dwordx4 v[236:239], v190, s[86:87] offset:896
	global_load_dwordx4 v[240:243], v191, s[86:87] offset:896
	global_load_dwordx4 v[244:247], v188, s[96:97] offset:896
	global_load_dwordx4 v[248:251], v188, s[98:99] offset:896
	ds_read_b128 v[90:93], v119 offset:20480
	ds_read_b128 v[208:211], v205 offset:40960
	ds_read_b128 v[212:215], v119 offset:23040
	ds_read_b128 v[216:219], v119 offset:25600
	ds_read_b128 v[220:223], v119 offset:28160
	s_waitcnt lgkmcnt(3)
	v_mfma_f32_16x16x32_bf16 v[6:9], v[90:93], v[208:211], v[6:9]
	s_waitcnt lgkmcnt(2)
	v_mfma_f32_16x16x32_bf16 v[30:33], v[212:215], v[208:211], v[30:33]
	s_waitcnt vmcnt(11)
	ds_write_b128 v206, v[66:69] offset:0
	s_waitcnt lgkmcnt(2)
	v_mfma_f32_16x16x32_bf16 v[38:41], v[216:219], v[208:211], v[38:41]
	s_waitcnt lgkmcnt(1)
	v_mfma_f32_16x16x32_bf16 v[42:45], v[220:223], v[208:211], v[42:45]
	ds_read_b128 v[208:211], v205 offset:43520
	s_waitcnt lgkmcnt(0)
	v_mfma_f32_16x16x32_bf16 v[46:49], v[90:93], v[208:211], v[46:49]
	v_mfma_f32_16x16x32_bf16 v[26:29], v[212:215], v[208:211], v[26:29]
	s_waitcnt vmcnt(10)
	ds_write_b128 v206, v[70:73] offset:10240
	v_mfma_f32_16x16x32_bf16 v[14:17], v[216:219], v[208:211], v[14:17]
	v_mfma_f32_16x16x32_bf16 v[10:13], v[220:223], v[208:211], v[10:13]
	ds_read_b128 v[208:211], v205 offset:46080
	s_waitcnt lgkmcnt(0)
	v_mfma_f32_16x16x32_bf16 v[34:37], v[90:93], v[208:211], v[34:37]
	v_mfma_f32_16x16x32_bf16 v[22:25], v[212:215], v[208:211], v[22:25]
	s_waitcnt vmcnt(9)
	ds_write_b128 v206, v[74:77] offset:20480
	v_mfma_f32_16x16x32_bf16 v[18:21], v[216:219], v[208:211], v[18:21]
	v_mfma_f32_16x16x32_bf16 v[62:65], v[220:223], v[208:211], v[62:65]
	ds_read_b128 v[208:211], v205 offset:48640
	s_waitcnt lgkmcnt(0)
	v_mfma_f32_16x16x32_bf16 v[58:61], v[90:93], v[208:211], v[58:61]
	ds_read_b128 v[90:93], v119 offset:20544
	v_mfma_f32_16x16x32_bf16 v[54:57], v[212:215], v[208:211], v[54:57]
	s_waitcnt vmcnt(8)
	ds_write_b128 v206, v[78:81] offset:30720
	ds_read_b128 v[212:215], v119 offset:23104
	v_mfma_f32_16x16x32_bf16 v[50:53], v[216:219], v[208:211], v[50:53]
	ds_read_b128 v[216:219], v119 offset:25664
	v_mfma_f32_16x16x32_bf16 v[2:5], v[220:223], v[208:211], v[2:5]
	ds_read_b128 v[220:223], v119 offset:28224
	ds_read_b128 v[208:211], v205 offset:41024
	ds_read_b128 v[224:227], v205 offset:48704
	s_waitcnt lgkmcnt(1)
	v_mfma_f32_16x16x32_bf16 v[6:9], v[90:93], v[208:211], v[6:9]
	v_mfma_f32_16x16x32_bf16 v[30:33], v[212:215], v[208:211], v[30:33]
	s_waitcnt vmcnt(7)
	ds_write_b128 v0, v[82:85] offset:0
	v_mfma_f32_16x16x32_bf16 v[38:41], v[216:219], v[208:211], v[38:41]
	v_mfma_f32_16x16x32_bf16 v[42:45], v[220:223], v[208:211], v[42:45]
	ds_read_b128 v[208:211], v205 offset:43584
	s_waitcnt lgkmcnt(0)
	v_mfma_f32_16x16x32_bf16 v[46:49], v[90:93], v[208:211], v[46:49]
	v_mfma_f32_16x16x32_bf16 v[26:29], v[212:215], v[208:211], v[26:29]
	s_waitcnt vmcnt(6)
	ds_write_b128 v0, v[86:89] offset:10240
	s_lshl_b32 s10, s66, 10
	s_mov_b32 s11, 0
	v_lshl_add_u64 v[82:83], v[128:129], 0, s[10:11]
	v_lshl_add_u64 v[84:85], v[132:133], 0, s[10:11]
	v_lshl_add_u64 v[86:87], v[152:153], 0, s[10:11]
	v_lshl_add_u64 v[88:89], v[154:155], 0, s[10:11]
	global_load_dwordx2 v[66:67], v[82:83], off
	global_load_dwordx2 v[68:69], v[82:83], off offset:32
	global_load_dwordx2 v[70:71], v[84:85], off
	global_load_dwordx2 v[72:73], v[84:85], off offset:32
	global_load_dwordx2 v[74:75], v[86:87], off
	global_load_dwordx2 v[76:77], v[86:87], off offset:32
	global_load_dwordx2 v[78:79], v[88:89], off
	global_load_dwordx2 v[80:81], v[88:89], off offset:32
	v_mfma_f32_16x16x32_bf16 v[14:17], v[216:219], v[208:211], v[14:17]
	v_mfma_f32_16x16x32_bf16 v[10:13], v[220:223], v[208:211], v[10:13]
	ds_read_b128 v[208:211], v205 offset:46144
	s_waitcnt lgkmcnt(0)
	v_mfma_f32_16x16x32_bf16 v[34:37], v[90:93], v[208:211], v[34:37]
	v_mfma_f32_16x16x32_bf16 v[22:25], v[212:215], v[208:211], v[22:25]
	v_mfma_f32_16x16x32_bf16 v[18:21], v[216:219], v[208:211], v[18:21]
	v_mfma_f32_16x16x32_bf16 v[62:65], v[220:223], v[208:211], v[62:65]
	v_mfma_f32_16x16x32_bf16 v[58:61], v[90:93], v[224:227], v[58:61]
	s_waitcnt lgkmcnt(0)
	v_mfma_f32_16x16x32_bf16 v[54:57], v[212:215], v[224:227], v[54:57]
	s_barrier
	v_mfma_f32_16x16x32_bf16 v[50:53], v[216:219], v[224:227], v[50:53]
	v_mfma_f32_16x16x32_bf16 v[2:5], v[220:223], v[224:227], v[2:5]
	ds_read_b128 v[90:93], v119 offset:0
	ds_read_b128 v[208:211], v205 offset:0
	ds_read_b128 v[212:215], v119 offset:2560
	ds_read_b128 v[216:219], v119 offset:5120
	ds_read_b128 v[220:223], v119 offset:7680
	s_waitcnt lgkmcnt(3)
	v_mfma_f32_16x16x32_bf16 v[6:9], v[90:93], v[208:211], v[6:9]
	s_waitcnt lgkmcnt(2)
	v_mfma_f32_16x16x32_bf16 v[30:33], v[212:215], v[208:211], v[30:33]
	s_waitcnt vmcnt(13)
	ds_write_b128 v207, v[228:231] offset:0
	s_waitcnt lgkmcnt(2)
	v_mfma_f32_16x16x32_bf16 v[38:41], v[216:219], v[208:211], v[38:41]
	s_waitcnt lgkmcnt(1)
	v_mfma_f32_16x16x32_bf16 v[42:45], v[220:223], v[208:211], v[42:45]
	ds_read_b128 v[208:211], v205 offset:2560
	s_waitcnt lgkmcnt(0)
	v_mfma_f32_16x16x32_bf16 v[46:49], v[90:93], v[208:211], v[46:49]
	v_mfma_f32_16x16x32_bf16 v[26:29], v[212:215], v[208:211], v[26:29]
	s_waitcnt vmcnt(12)
	ds_write_b128 v207, v[232:235] offset:10240
	v_mfma_f32_16x16x32_bf16 v[14:17], v[216:219], v[208:211], v[14:17]
	v_mfma_f32_16x16x32_bf16 v[10:13], v[220:223], v[208:211], v[10:13]
	ds_read_b128 v[208:211], v205 offset:5120
	s_waitcnt lgkmcnt(0)
	v_mfma_f32_16x16x32_bf16 v[34:37], v[90:93], v[208:211], v[34:37]
	v_mfma_f32_16x16x32_bf16 v[22:25], v[212:215], v[208:211], v[22:25]
	s_waitcnt vmcnt(11)
	ds_write_b128 v207, v[236:239] offset:20480
	v_mfma_f32_16x16x32_bf16 v[18:21], v[216:219], v[208:211], v[18:21]
	v_mfma_f32_16x16x32_bf16 v[62:65], v[220:223], v[208:211], v[62:65]
	ds_read_b128 v[208:211], v205 offset:7680
	s_waitcnt lgkmcnt(0)
	v_mfma_f32_16x16x32_bf16 v[58:61], v[90:93], v[208:211], v[58:61]
	ds_read_b128 v[90:93], v119 offset:64
	v_mfma_f32_16x16x32_bf16 v[54:57], v[212:215], v[208:211], v[54:57]
	s_waitcnt vmcnt(10)
	ds_write_b128 v207, v[240:243] offset:30720
	ds_read_b128 v[212:215], v119 offset:2624
	v_mfma_f32_16x16x32_bf16 v[50:53], v[216:219], v[208:211], v[50:53]
	ds_read_b128 v[216:219], v119 offset:5184
	v_mfma_f32_16x16x32_bf16 v[2:5], v[220:223], v[208:211], v[2:5]
	ds_read_b128 v[220:223], v119 offset:7744
	ds_read_b128 v[208:211], v205 offset:64
	ds_read_b128 v[224:227], v205 offset:7744
	s_waitcnt lgkmcnt(1)
	v_mfma_f32_16x16x32_bf16 v[6:9], v[90:93], v[208:211], v[6:9]
	v_mfma_f32_16x16x32_bf16 v[30:33], v[212:215], v[208:211], v[30:33]
	s_waitcnt vmcnt(9)
	ds_write_b128 v0, v[244:247] offset:20480
	v_mfma_f32_16x16x32_bf16 v[38:41], v[216:219], v[208:211], v[38:41]
	v_mfma_f32_16x16x32_bf16 v[42:45], v[220:223], v[208:211], v[42:45]
	ds_read_b128 v[208:211], v205 offset:2624
	s_waitcnt lgkmcnt(0)
	v_mfma_f32_16x16x32_bf16 v[46:49], v[90:93], v[208:211], v[46:49]
	v_mfma_f32_16x16x32_bf16 v[26:29], v[212:215], v[208:211], v[26:29]
	s_waitcnt vmcnt(8)
	ds_write_b128 v0, v[248:251] offset:30720
	v_mfma_f32_16x16x32_bf16 v[14:17], v[216:219], v[208:211], v[14:17]
	v_mfma_f32_16x16x32_bf16 v[10:13], v[220:223], v[208:211], v[10:13]
	ds_read_b128 v[208:211], v205 offset:5184
	s_waitcnt lgkmcnt(0)
	v_mfma_f32_16x16x32_bf16 v[34:37], v[90:93], v[208:211], v[34:37]
	v_mfma_f32_16x16x32_bf16 v[22:25], v[212:215], v[208:211], v[22:25]
	v_mfma_f32_16x16x32_bf16 v[18:21], v[216:219], v[208:211], v[18:21]
	v_mfma_f32_16x16x32_bf16 v[62:65], v[220:223], v[208:211], v[62:65]
	v_mfma_f32_16x16x32_bf16 v[58:61], v[90:93], v[224:227], v[58:61]
	s_waitcnt lgkmcnt(0)
	v_mfma_f32_16x16x32_bf16 v[54:57], v[212:215], v[224:227], v[54:57]
	s_barrier
	v_mfma_f32_16x16x32_bf16 v[50:53], v[216:219], v[224:227], v[50:53]
	v_mfma_f32_16x16x32_bf16 v[2:5], v[220:223], v[224:227], v[2:5]
	ds_read_b128 v[90:93], v119 offset:20480
	ds_read_b128 v[208:211], v205 offset:40960
	ds_read_b128 v[212:215], v119 offset:23040
	ds_read_b128 v[216:219], v119 offset:25600
	ds_read_b128 v[220:223], v119 offset:28160
	s_waitcnt lgkmcnt(3)
	v_mfma_f32_16x16x32_bf16 v[6:9], v[90:93], v[208:211], v[6:9]
	s_waitcnt lgkmcnt(2)
	v_mfma_f32_16x16x32_bf16 v[30:33], v[212:215], v[208:211], v[30:33]
	s_waitcnt lgkmcnt(1)
	v_mfma_f32_16x16x32_bf16 v[38:41], v[216:219], v[208:211], v[38:41]
	s_waitcnt lgkmcnt(0)
	v_mfma_f32_16x16x32_bf16 v[42:45], v[220:223], v[208:211], v[42:45]
	ds_read_b128 v[208:211], v205 offset:43520
	s_waitcnt lgkmcnt(0)
	v_mfma_f32_16x16x32_bf16 v[46:49], v[90:93], v[208:211], v[46:49]
	v_mfma_f32_16x16x32_bf16 v[26:29], v[212:215], v[208:211], v[26:29]
	v_mfma_f32_16x16x32_bf16 v[14:17], v[216:219], v[208:211], v[14:17]
	v_mfma_f32_16x16x32_bf16 v[10:13], v[220:223], v[208:211], v[10:13]
	ds_read_b128 v[208:211], v205 offset:46080
	s_waitcnt lgkmcnt(0)
	v_mfma_f32_16x16x32_bf16 v[34:37], v[90:93], v[208:211], v[34:37]
	v_mfma_f32_16x16x32_bf16 v[22:25], v[212:215], v[208:211], v[22:25]
	v_mfma_f32_16x16x32_bf16 v[18:21], v[216:219], v[208:211], v[18:21]
	v_mfma_f32_16x16x32_bf16 v[62:65], v[220:223], v[208:211], v[62:65]
	ds_read_b128 v[208:211], v205 offset:48640
	s_waitcnt lgkmcnt(0)
	v_mfma_f32_16x16x32_bf16 v[58:61], v[90:93], v[208:211], v[58:61]
	ds_read_b128 v[90:93], v119 offset:20544
	v_mfma_f32_16x16x32_bf16 v[54:57], v[212:215], v[208:211], v[54:57]
	ds_read_b128 v[212:215], v119 offset:23104
	v_mfma_f32_16x16x32_bf16 v[50:53], v[216:219], v[208:211], v[50:53]
	ds_read_b128 v[216:219], v119 offset:25664
	v_mfma_f32_16x16x32_bf16 v[2:5], v[220:223], v[208:211], v[2:5]
	ds_read_b128 v[220:223], v119 offset:28224
	ds_read_b128 v[208:211], v205 offset:41024
	ds_read_b128 v[224:227], v205 offset:48704
	s_waitcnt lgkmcnt(1)
	v_mfma_f32_16x16x32_bf16 v[6:9], v[90:93], v[208:211], v[6:9]
	s_waitcnt vmcnt(0)
	v_mfma_f32_16x16x32_bf16 v[30:33], v[212:215], v[208:211], v[30:33]
	v_mfma_f32_16x16x32_bf16 v[38:41], v[216:219], v[208:211], v[38:41]
	v_mfma_f32_16x16x32_bf16 v[42:45], v[220:223], v[208:211], v[42:45]
	v_cvt_f32_ubyte0_e32 v86, v66
	v_cvt_f32_ubyte1_e32 v87, v66
	v_cvt_f32_ubyte2_e32 v88, v66
	v_cvt_f32_ubyte3_e32 v89, v66
	v_mul_f32_e32 v86, s34, v86
	v_mul_f32_e32 v87, s34, v87
	v_mul_f32_e32 v88, s34, v88
	v_mul_f32_e32 v89, s34, v89
	v_fma_f32 v184, v6, v86, v184
	v_fma_f32 v185, v7, v87, v185
	v_fma_f32 v186, v8, v88, v186
	v_fma_f32 v187, v9, v89, v187
	ds_read_b128 v[208:211], v205 offset:43584
	s_waitcnt lgkmcnt(0)
	v_mfma_f32_16x16x32_bf16 v[46:49], v[90:93], v[208:211], v[46:49]
	v_cvt_f32_ubyte0_e32 v82, v67
	v_cvt_f32_ubyte1_e32 v83, v67
	v_cvt_f32_ubyte2_e32 v84, v67
	v_cvt_f32_ubyte3_e32 v85, v67
	v_mul_f32_e32 v82, s34, v82
	v_mul_f32_e32 v83, s34, v83
	v_mul_f32_e32 v84, s34, v84
	v_mul_f32_e32 v85, s34, v85
	v_fma_f32 v180, v30, v82, v180
	v_fma_f32 v181, v31, v83, v181
	v_fma_f32 v182, v32, v84, v182
	v_fma_f32 v183, v33, v85, v183
	v_mfma_f32_16x16x32_bf16 v[26:29], v[212:215], v[208:211], v[26:29]
	v_cvt_f32_ubyte0_e32 v86, v68
	v_cvt_f32_ubyte1_e32 v87, v68
	v_cvt_f32_ubyte2_e32 v88, v68
	v_cvt_f32_ubyte3_e32 v89, v68
	v_mul_f32_e32 v86, s34, v86
	v_mul_f32_e32 v87, s34, v87
	v_mul_f32_e32 v88, s34, v88
	v_mul_f32_e32 v89, s34, v89
	v_fma_f32 v176, v38, v86, v176
	v_fma_f32 v177, v39, v87, v177
	v_fma_f32 v178, v40, v88, v178
	v_fma_f32 v179, v41, v89, v179
	v_mfma_f32_16x16x32_bf16 v[14:17], v[216:219], v[208:211], v[14:17]
	v_cvt_f32_ubyte0_e32 v82, v69
	v_cvt_f32_ubyte1_e32 v83, v69
	v_cvt_f32_ubyte2_e32 v84, v69
	v_cvt_f32_ubyte3_e32 v85, v69
	v_mul_f32_e32 v82, s34, v82
	v_mul_f32_e32 v83, s34, v83
	v_mul_f32_e32 v84, s34, v84
	v_mul_f32_e32 v85, s34, v85
	v_fma_f32 v172, v42, v82, v172
	v_fma_f32 v173, v43, v83, v173
	v_fma_f32 v174, v44, v84, v174
	v_fma_f32 v175, v45, v85, v175
	v_mfma_f32_16x16x32_bf16 v[10:13], v[220:223], v[208:211], v[10:13]
	v_cvt_f32_ubyte0_e32 v86, v70
	v_cvt_f32_ubyte1_e32 v87, v70
	v_cvt_f32_ubyte2_e32 v88, v70
	v_cvt_f32_ubyte3_e32 v89, v70
	v_mul_f32_e32 v86, s34, v86
	v_mul_f32_e32 v87, s34, v87
	v_mul_f32_e32 v88, s34, v88
	v_mul_f32_e32 v89, s34, v89
	v_fma_f32 v168, v46, v86, v168
	v_fma_f32 v169, v47, v87, v169
	v_fma_f32 v170, v48, v88, v170
	v_fma_f32 v171, v49, v89, v171
	ds_read_b128 v[208:211], v205 offset:46144
	s_waitcnt lgkmcnt(0)
	v_mfma_f32_16x16x32_bf16 v[34:37], v[90:93], v[208:211], v[34:37]
	v_cvt_f32_ubyte0_e32 v82, v71
	v_cvt_f32_ubyte1_e32 v83, v71
	v_cvt_f32_ubyte2_e32 v84, v71
	v_cvt_f32_ubyte3_e32 v85, v71
	v_mul_f32_e32 v82, s34, v82
	v_mul_f32_e32 v83, s34, v83
	v_mul_f32_e32 v84, s34, v84
	v_mul_f32_e32 v85, s34, v85
	v_fma_f32 v164, v26, v82, v164
	v_fma_f32 v165, v27, v83, v165
	v_fma_f32 v166, v28, v84, v166
	v_fma_f32 v167, v29, v85, v167
	v_mfma_f32_16x16x32_bf16 v[22:25], v[212:215], v[208:211], v[22:25]
	v_cvt_f32_ubyte0_e32 v86, v72
	v_cvt_f32_ubyte1_e32 v87, v72
	v_cvt_f32_ubyte2_e32 v88, v72
	v_cvt_f32_ubyte3_e32 v89, v72
	v_mul_f32_e32 v86, s34, v86
	v_mul_f32_e32 v87, s34, v87
	v_mul_f32_e32 v88, s34, v88
	v_mul_f32_e32 v89, s34, v89
	v_fma_f32 v160, v14, v86, v160
	v_fma_f32 v161, v15, v87, v161
	v_fma_f32 v162, v16, v88, v162
	v_fma_f32 v163, v17, v89, v163
	v_mfma_f32_16x16x32_bf16 v[18:21], v[216:219], v[208:211], v[18:21]
	v_cvt_f32_ubyte0_e32 v82, v73
	v_cvt_f32_ubyte1_e32 v83, v73
	v_cvt_f32_ubyte2_e32 v84, v73
	v_cvt_f32_ubyte3_e32 v85, v73
	v_mul_f32_e32 v82, s34, v82
	v_mul_f32_e32 v83, s34, v83
	v_mul_f32_e32 v84, s34, v84
	v_mul_f32_e32 v85, s34, v85
	v_fma_f32 v156, v10, v82, v156
	v_fma_f32 v157, v11, v83, v157
	v_fma_f32 v158, v12, v84, v158
	v_fma_f32 v159, v13, v85, v159
	v_mfma_f32_16x16x32_bf16 v[62:65], v[220:223], v[208:211], v[62:65]
	v_cvt_f32_ubyte0_e32 v86, v74
	v_cvt_f32_ubyte1_e32 v87, v74
	v_cvt_f32_ubyte2_e32 v88, v74
	v_cvt_f32_ubyte3_e32 v89, v74
	v_mul_f32_e32 v86, s34, v86
	v_mul_f32_e32 v87, s34, v87
	v_mul_f32_e32 v88, s34, v88
	v_mul_f32_e32 v89, s34, v89
	v_fma_f32 v136, v34, v86, v136
	v_fma_f32 v137, v35, v87, v137
	v_fma_f32 v150, v36, v88, v150
	v_fma_f32 v151, v37, v89, v151
	v_mfma_f32_16x16x32_bf16 v[58:61], v[90:93], v[224:227], v[58:61]
	v_cvt_f32_ubyte0_e32 v82, v75
	v_cvt_f32_ubyte1_e32 v83, v75
	v_cvt_f32_ubyte2_e32 v84, v75
	v_cvt_f32_ubyte3_e32 v85, v75
	v_mul_f32_e32 v82, s34, v82
	v_mul_f32_e32 v83, s34, v83
	v_mul_f32_e32 v84, s34, v84
	v_mul_f32_e32 v85, s34, v85
	v_fma_f32 v130, v22, v82, v130
	v_fma_f32 v131, v23, v83, v131
	v_fma_f32 v134, v24, v84, v134
	v_fma_f32 v135, v25, v85, v135
	v_mfma_f32_16x16x32_bf16 v[54:57], v[212:215], v[224:227], v[54:57]
	v_cvt_f32_ubyte0_e32 v86, v76
	v_cvt_f32_ubyte1_e32 v87, v76
	v_cvt_f32_ubyte2_e32 v88, v76
	v_cvt_f32_ubyte3_e32 v89, v76
	v_mul_f32_e32 v86, s34, v86
	v_mul_f32_e32 v87, s34, v87
	v_mul_f32_e32 v88, s34, v88
	v_mul_f32_e32 v89, s34, v89
	v_fma_f32 v124, v18, v86, v124
	v_fma_f32 v125, v19, v87, v125
	v_fma_f32 v126, v20, v88, v126
	v_fma_f32 v127, v21, v89, v127
	v_mfma_f32_16x16x32_bf16 v[50:53], v[216:219], v[224:227], v[50:53]
	v_cvt_f32_ubyte0_e32 v82, v77
	v_cvt_f32_ubyte1_e32 v83, v77
	v_cvt_f32_ubyte2_e32 v84, v77
	v_cvt_f32_ubyte3_e32 v85, v77
	v_mul_f32_e32 v82, s34, v82
	v_mul_f32_e32 v83, s34, v83
	v_mul_f32_e32 v84, s34, v84
	v_mul_f32_e32 v85, s34, v85
	v_fma_f32 v120, v62, v82, v120
	v_fma_f32 v121, v63, v83, v121
	v_fma_f32 v122, v64, v84, v122
	v_fma_f32 v123, v65, v85, v123
	v_mfma_f32_16x16x32_bf16 v[2:5], v[220:223], v[224:227], v[2:5]
	v_cvt_f32_ubyte0_e32 v86, v78
	v_cvt_f32_ubyte1_e32 v87, v78
	v_cvt_f32_ubyte2_e32 v88, v78
	v_cvt_f32_ubyte3_e32 v89, v78
	v_mul_f32_e32 v86, s34, v86
	v_mul_f32_e32 v87, s34, v87
	v_mul_f32_e32 v88, s34, v88
	v_mul_f32_e32 v89, s34, v89
	v_fma_f32 v114, v58, v86, v114
	v_fma_f32 v115, v59, v87, v115
	v_fma_f32 v116, v60, v88, v116
	v_fma_f32 v117, v61, v89, v117
	s_nop 7
	s_nop 3
	v_cvt_f32_ubyte0_e32 v86, v79
	v_cvt_f32_ubyte1_e32 v87, v79
	v_cvt_f32_ubyte2_e32 v88, v79
	v_cvt_f32_ubyte3_e32 v89, v79
	v_mul_f32_e32 v86, s34, v86
	v_mul_f32_e32 v87, s34, v87
	v_mul_f32_e32 v88, s34, v88
	v_mul_f32_e32 v89, s34, v89
	v_fma_f32 v106, v54, v86, v106
	v_fma_f32 v107, v55, v87, v107
	v_fma_f32 v108, v56, v88, v108
	v_fma_f32 v109, v57, v89, v109
	v_cvt_f32_ubyte0_e32 v82, v80
	v_cvt_f32_ubyte1_e32 v83, v80
	v_cvt_f32_ubyte2_e32 v84, v80
	v_cvt_f32_ubyte3_e32 v85, v80
	v_mul_f32_e32 v82, s34, v82
	v_mul_f32_e32 v83, s34, v83
	v_mul_f32_e32 v84, s34, v84
	v_mul_f32_e32 v85, s34, v85
	v_fma_f32 v100, v50, v82, v100
	v_fma_f32 v101, v51, v83, v101
	v_fma_f32 v102, v52, v84, v102
	v_fma_f32 v103, v53, v85, v103
	v_cvt_f32_ubyte0_e32 v86, v81
	v_cvt_f32_ubyte1_e32 v87, v81
	v_cvt_f32_ubyte2_e32 v88, v81
	v_cvt_f32_ubyte3_e32 v89, v81
	v_mul_f32_e32 v86, s34, v86
	v_mul_f32_e32 v87, s34, v87
	v_mul_f32_e32 v88, s34, v88
	v_mul_f32_e32 v89, s34, v89
	v_fma_f32 v96, v2, v86, v96
	v_fma_f32 v97, v3, v87, v97
	v_fma_f32 v98, v4, v88, v98
	v_fma_f32 v99, v5, v89, v99
	s_add_i32 s66, s66, 1
	s_add_u32 s6, s6, 0x100000
	s_addc_u32 s7, s7, 0
	s_cmp_eq_u32 s66, 4
	s_cbranch_scc0 .LBB0_1004
	v_lshlrev_b32_e32 v0, 1, v118
	v_lshl_add_u64 v[6:7], s[4:5], 0, v[0:1]
	v_lshlrev_b64 v[2:3], 11, v[112:113]
	v_lshl_add_u64 v[8:9], v[6:7], 0, v[2:3]
	v_cvt_pk_bf16_f32 v2, v184, v185
	v_cvt_pk_bf16_f32 v3, v186, v187
	v_cvt_pk_bf16_f32 v4, v180, v181
	v_cvt_pk_bf16_f32 v5, v182, v183
	global_store_dwordx4 v[8:9], v[2:5], off
	v_readlane_b32 s46, v254, 29
	s_mov_b32 s38, 0
	v_cvt_pk_bf16_f32 v2, v176, v177
	v_cvt_pk_bf16_f32 v3, v178, v179
	v_cvt_pk_bf16_f32 v4, v172, v173
	v_cvt_pk_bf16_f32 v5, v174, v175
	global_store_dwordx4 v[8:9], v[2:5], off offset:64
	v_readlane_b32 s47, v254, 30
	s_nop 0
	v_lshlrev_b64 v[2:3], 11, v[110:111]
	v_lshl_add_u64 v[8:9], v[6:7], 0, v[2:3]
	v_cvt_pk_bf16_f32 v2, v168, v169
	v_cvt_pk_bf16_f32 v3, v170, v171
	v_cvt_pk_bf16_f32 v4, v164, v165
	v_cvt_pk_bf16_f32 v5, v166, v167
	global_store_dwordx4 v[8:9], v[2:5], off
	s_nop 1
	v_cvt_pk_bf16_f32 v2, v160, v161
	v_cvt_pk_bf16_f32 v3, v162, v163
	v_cvt_pk_bf16_f32 v4, v156, v157
	v_cvt_pk_bf16_f32 v5, v158, v159
	global_store_dwordx4 v[8:9], v[2:5], off offset:64
	s_nop 1
	v_lshlrev_b64 v[2:3], 11, v[104:105]
	v_lshl_add_u64 v[8:9], v[6:7], 0, v[2:3]
	v_cvt_pk_bf16_f32 v2, v136, v137
	v_cvt_pk_bf16_f32 v3, v150, v151
	v_cvt_pk_bf16_f32 v4, v130, v131
	v_cvt_pk_bf16_f32 v5, v134, v135
	global_store_dwordx4 v[8:9], v[2:5], off
	s_nop 1
	v_cvt_pk_bf16_f32 v2, v124, v125
	v_cvt_pk_bf16_f32 v3, v126, v127
	v_cvt_pk_bf16_f32 v4, v120, v121
	v_cvt_pk_bf16_f32 v5, v122, v123
	global_store_dwordx4 v[8:9], v[2:5], off offset:64
	s_nop 1
	v_lshlrev_b64 v[2:3], 11, v[94:95]
	v_lshl_add_u64 v[6:7], v[6:7], 0, v[2:3]
	v_cvt_pk_bf16_f32 v2, v114, v115
	v_cvt_pk_bf16_f32 v3, v116, v117
	v_cvt_pk_bf16_f32 v4, v106, v107
	v_cvt_pk_bf16_f32 v5, v108, v109
	global_store_dwordx4 v[6:7], v[2:5], off
	s_nop 1
	v_cvt_pk_bf16_f32 v2, v100, v101
	v_cvt_pk_bf16_f32 v3, v102, v103
	v_cvt_pk_bf16_f32 v4, v96, v97
	v_cvt_pk_bf16_f32 v5, v98, v99
	global_store_dwordx4 v[6:7], v[2:5], off offset:64
